# prep: the two half-workgroup job streams run one barrier apart (same idea as the walks)
# baseline (speedup 1.0000x reference)
.LBB0_564:
	s_andn2_b64 vcc, exec, s[2:3]
	s_cbranch_vccnz .LBB0_687
	s_cmp_lt_i32 s57, 1
	s_mov_b64 s[2:3], -1
	s_cbranch_scc1 .LBB0_678
	s_cmp_gt_i32 s57, 1
	s_cbranch_scc0 .LBB0_664
	v_readfirstlane_b32 s100, v158
	s_lshr_b32 s100, s100, 8
	s_cmp_eq_u32 s100, 1
	s_cbranch_scc0 .Lpoff_a
	s_barrier
.Lpoff_a:
	v_ashrrev_i32_e32 v122, 8, v158
	v_and_b32_e32 v123, 0xff, v158
	v_mul_i32_i24_e32 v93, 0x12c00, v122
	s_waitcnt lgkmcnt(0)
	s_barrier
	v_lshl_or_b32 v95, v123, 1, v93
	s_add_i32 s1, 0, 0x5000
	v_add_u32_e32 v0, s1, v95
	s_waitcnt vmcnt(0)
	v_or_b32_e32 v2, 0xffffff00, v123
	s_mov_b64 s[2:3], 0
	s_movk_i32 s1, 0x22ff

.LBB0_663:
	v_readfirstlane_b32 s100, v158
	s_lshr_b32 s100, s100, 8
	s_cmp_eq_u32 s100, 0
	s_cbranch_scc0 .Lpoff_b
	s_barrier

	.amdhsa_kernel _Z4mega6Params
		.amdhsa_group_segment_fixed_size 0
		.amdhsa_private_segment_fixed_size 0
		.amdhsa_kernarg_size 632
		.amdhsa_user_sgpr_count 2
		.amdhsa_user_sgpr_dispatch_ptr 0
		.amdhsa_user_sgpr_queue_ptr 0
		.amdhsa_user_sgpr_kernarg_segment_ptr 1
		.amdhsa_user_sgpr_dispatch_id 0
		.amdhsa_user_sgpr_kernarg_preload_length 0
		.amdhsa_user_sgpr_kernarg_preload_offset 0
		.amdhsa_user_sgpr_private_segment_size 0
		.amdhsa_uses_dynamic_stack 0
		.amdhsa_enable_private_segment 0
		.amdhsa_system_sgpr_workgroup_id_x 1
		.amdhsa_system_sgpr_workgroup_id_y 0
		.amdhsa_system_sgpr_workgroup_id_z 0
		.amdhsa_system_sgpr_workgroup_info 0
		.amdhsa_system_vgpr_workitem_id 2
		.amdhsa_next_free_vgpr 256
		.amdhsa_next_free_sgpr 102
		.amdhsa_accum_offset 256
		.amdhsa_reserve_vcc 1
		.amdhsa_float_round_mode_32 0
		.amdhsa_float_round_mode_16_64 0
		.amdhsa_float_denorm_mode_32 3
		.amdhsa_float_denorm_mode_16_64 3
		.amdhsa_dx10_clamp 1
		.amdhsa_ieee_mode 1
		.amdhsa_fp16_overflow 0
		.amdhsa_tg_split 0
		.amdhsa_exception_fp_ieee_invalid_op 0
		.amdhsa_exception_fp_denorm_src 0
		.amdhsa_exception_fp_ieee_div_zero 0
		.amdhsa_exception_fp_ieee_overflow 0
		.amdhsa_exception_fp_ieee_underflow 0
		.amdhsa_exception_fp_ieee_inexact 0
		.amdhsa_exception_int_div_zero 0
	.end_amdhsa_kernel

amdhsa.kernels:
  - .agpr_count:     0
    .args:
      - .offset:         0
        .size:           376
        .value_kind:     by_value
      - .offset:         376
        .size:           4
        .value_kind:     hidden_block_count_x
      - .offset:         380
        .size:           4
        .value_kind:     hidden_block_count_y
      - .offset:         384
        .size:           4
        .value_kind:     hidden_block_count_z
      - .offset:         388
        .size:           2
        .value_kind:     hidden_group_size_x
      - .offset:         390
        .size:           2
        .value_kind:     hidden_group_size_y
      - .offset:         392
        .size:           2
        .value_kind:     hidden_group_size_z
      - .offset:         394
        .size:           2
        .value_kind:     hidden_remainder_x
      - .offset:         396
        .size:           2
        .value_kind:     hidden_remainder_y
      - .offset:         398
        .size:           2
        .value_kind:     hidden_remainder_z
      - .offset:         416
        .size:           8
        .value_kind:     hidden_global_offset_x
      - .offset:         424
        .size:           8
        .value_kind:     hidden_global_offset_y
      - .offset:         432
        .size:           8
        .value_kind:     hidden_global_offset_z
      - .offset:         440
        .size:           2
        .value_kind:     hidden_grid_dims
      - .offset:         464
        .size:           8
        .value_kind:     hidden_multigrid_sync_arg
      - .offset:         496
        .size:           4
        .value_kind:     hidden_dynamic_lds_size
    .group_segment_fixed_size: 0
    .kernarg_segment_align: 8
    .kernarg_segment_size: 632
    .language:       OpenCL C
    .language_version:
      - 2
      - 0
    .max_flat_workgroup_size: 512
    .name:           _Z4mega6Params
    .private_segment_fixed_size: 0
    .sgpr_count:     108
    .sgpr_spill_count: 91
    .symbol:         _Z4mega6Params.kd
    .uniform_work_group_size: 1
    .uses_dynamic_stack: false
    .vgpr_count:     256
    .vgpr_spill_count: 0
    .wavefront_size: 64
